# natten window softmax: exec-masked per-element LDS bias ladder (16 serial round trips per tile) replaced by pipelined unconditional reads + v_cndmask
# baseline (speedup 1.0000x reference)
; template <bool WIN> __device__ __forceinline__ void partialSM(f32x16& p0, f32x16& p1, float& m_reg, float& mn, float& alpha, bool rowok, const float* tb, int t0) {
;   if (WIN) {
;     if (rowok) {
; #pragma unroll
;       for (int r = 0; r < 16; ++r) { const int cr = (r & 3) + 8 * (r >> 2);
;         const float b0 = tb[cr], b1 = tb[cr + 32];
;         p0[r] = ((unsigned)(cr + t0) < 16u) ? fmaf(p0[r], C2, b0) : NEGB;
;         p1[r] = ((unsigned)(cr + 32 + t0) < 16u) ? fmaf(p1[r], C2, b1) : NEGB; }
;     } else {
; #pragma unroll
;       for (int r = 0; r < 16; ++r) { p0[r] = NEGB; p1[r] = NEGB; }
;     }
;   } else {
; #pragma unroll
;     for (int r = 0; r < 16; ++r) { p0[r] *= C2; p1[r] *= C2; }
;   }
;   float pmax = p0[0];
; #pragma unroll
;   for (int r = 1; r < 16; ++r) pmax = fmaxf(pmax, p0[r]);
; #pragma unroll
;   for (int r = 0; r < 16; ++r) pmax = fmaxf(pmax, p1[r]);
;   { auto rr = __builtin_amdgcn_permlane32_swap(__float_as_uint(pmax), __float_as_uint(pmax), false, false);
;     pmax = fmaxf(__uint_as_float(rr[0]), __uint_as_float(rr[1])); }
;   if (__builtin_expect(__all(pmax - m_reg <= THR2), 1)) { mn = m_reg; alpha = 1.f; }
; __device__ __forceinline__ void natten_unit(const bf16* __restrict__ P, bf16* __restrict__ Y, const float* __restrict__ rpbh, long qrow0, long crow0, long wrow0, int h, int NT, bool win, int r0, int ws0, char* lds, int tid) {
;     ...
;         else { const int dr_ = min(max(kr_ - qgr + 7, 0), 14); partialSM<true>(p0, p1, m_reg, mn, al, true, tbl + dr_ * NAT_TABW, t0); }
.LBB0_977:
	s_andn2_b64 vcc, exec, s[16:17]
	s_cbranch_vccnz .LBB0_1011
	s_add_i32 s0, s29, s35
	s_max_i32 s0, s0, -7
	s_add_i32 s0, s0, 7
	s_min_u32 s0, s0, 14
	s_lshl_b32 s0, s0, 9
	v_add_u32_e32 v184, s0, v228
	ds_read_b32 v155, v184
	ds_read_b32 v152, v184 offset:4
	ds_read_b32 v153, v184 offset:8
	ds_read_b32 v156, v184 offset:12
	ds_read_b32 v157, v184 offset:32
	ds_read_b32 v158, v184 offset:36
	ds_read_b32 v159, v184 offset:40
	ds_read_b32 v154, v184 offset:128
	s_waitcnt lgkmcnt(7)
	v_fmac_f32_e32 v155, 0x3e0293ee, v82
	v_cndmask_b32_e64 v155, v206, v155, s[46:47]
	ds_read_b32 v82, v184 offset:132
	ds_read_b32 v160, v184 offset:44
	s_waitcnt lgkmcnt(8)
	v_fmac_f32_e32 v152, 0x3e0293ee, v83
	v_cndmask_b32_e64 v152, v206, v152, s[50:51]
	ds_read_b32 v83, v184 offset:136
	ds_read_b32 v161, v184 offset:64
	s_waitcnt lgkmcnt(9)
	v_fmac_f32_e32 v153, 0x3e0293ee, v84
	v_cndmask_b32_e64 v153, v206, v153, s[54:55]
	ds_read_b32 v84, v184 offset:140
	ds_read_b32 v178, v184 offset:68
	s_waitcnt lgkmcnt(10)
	v_fmac_f32_e32 v156, 0x3e0293ee, v85
	v_cndmask_b32_e64 v156, v206, v156, s[58:59]
	ds_read_b32 v85, v184 offset:160
	ds_read_b32 v179, v184 offset:72
	s_waitcnt lgkmcnt(11)
	v_fmac_f32_e32 v157, 0x3e0293ee, v86
	v_cndmask_b32_e64 v157, v206, v157, s[62:63]
	ds_read_b32 v86, v184 offset:164
	ds_read_b32 v180, v184 offset:76
	s_waitcnt lgkmcnt(12)
	v_fmac_f32_e32 v158, 0x3e0293ee, v87
	v_cndmask_b32_e64 v158, v206, v158, s[66:67]
	ds_read_b32 v87, v184 offset:168
	ds_read_b32 v181, v184 offset:96
	s_waitcnt lgkmcnt(13)
	v_fmac_f32_e32 v159, 0x3e0293ee, v88
	v_cndmask_b32_e64 v159, v206, v159, s[70:71]
	ds_read_b32 v88, v184 offset:172
	ds_read_b32 v182, v184 offset:100
	s_waitcnt lgkmcnt(12)
	v_fmac_f32_e32 v160, 0x3e0293ee, v89
	v_cndmask_b32_e64 v160, v206, v160, s[74:75]
	ds_read_b32 v89, v184 offset:192
	ds_read_b32 v183, v184 offset:104
	s_waitcnt lgkmcnt(12)
	v_fmac_f32_e32 v161, 0x3e0293ee, v90
	v_cndmask_b32_e64 v161, v206, v161, s[78:79]
	ds_read_b32 v90, v184 offset:196
	ds_read_b32 v233, v184 offset:108
	s_waitcnt lgkmcnt(12)
	v_fmac_f32_e32 v178, 0x3e0293ee, v91
	v_cndmask_b32_e64 v178, v206, v178, s[82:83]
	ds_read_b32 v91, v184 offset:200
	s_waitcnt lgkmcnt(11)
	v_fmac_f32_e32 v179, 0x3e0293ee, v92
	v_cndmask_b32_e64 v179, v206, v179, s[86:87]
	ds_read_b32 v92, v184 offset:204
	s_waitcnt lgkmcnt(10)
	v_fmac_f32_e32 v180, 0x3e0293ee, v93
	v_cndmask_b32_e64 v180, v206, v180, s[90:91]
	ds_read_b32 v93, v184 offset:224
	ds_read_b32 v185, v184 offset:228
	s_waitcnt lgkmcnt(10)
	v_fmac_f32_e32 v181, 0x3e0293ee, v94
	v_cndmask_b32_e64 v181, v206, v181, s[94:95]
	s_waitcnt lgkmcnt(8)
	v_fmac_f32_e32 v182, 0x3e0293ee, v95
	v_cndmask_b32_e64 v182, v206, v182, s[2:3]
	ds_read_b32 v95, v184 offset:232
	ds_read_b32 v94, v184 offset:236
	s_waitcnt lgkmcnt(8)
	v_fmac_f32_e32 v183, 0x3e0293ee, v96
	v_cndmask_b32_e64 v183, v206, v183, s[6:7]
	s_waitcnt lgkmcnt(6)
	v_fmac_f32_e32 v233, 0x3e0293ee, v97
	v_cndmask_b32_e64 v233, v206, v233, s[10:11]
	s_waitcnt lgkmcnt(14)
	v_fmac_f32_e32 v82, 0x3e0293ee, v67
	v_fmac_f32_e32 v154, 0x3e0293ee, v66
	v_max_f32_e32 v66, v152, v152
	v_max_f32_e32 v67, v155, v155
	v_max_f32_e32 v66, v67, v66
	v_max3_f32 v66, v66, v153, v156
	v_max3_f32 v66, v66, v157, v158
	v_max3_f32 v66, v66, v159, v160
	v_max3_f32 v66, v66, v161, v178
	v_max3_f32 v66, v66, v179, v180
	s_waitcnt lgkmcnt(2)
	v_fmac_f32_e32 v185, 0x3e0293ee, v79
	v_max3_f32 v66, v66, v181, v182
	v_cndmask_b32_e64 v197, v206, v185, s[4:5]
	v_fmac_f32_e32 v84, 0x3e0293ee, v69
	v_fmac_f32_e32 v83, 0x3e0293ee, v68
	v_cndmask_b32_e64 v185, v206, v82, s[52:53]
	v_cndmask_b32_e64 v184, v206, v154, s[48:49]
	v_max3_f32 v66, v66, v183, v233
	v_fmac_f32_e32 v86, 0x3e0293ee, v71
	v_fmac_f32_e32 v85, 0x3e0293ee, v70
	v_cndmask_b32_e64 v187, v206, v84, s[60:61]
	v_cndmask_b32_e64 v186, v206, v83, s[56:57]
	v_max3_f32 v66, v66, v184, v185
	v_fmac_f32_e32 v88, 0x3e0293ee, v73
	v_fmac_f32_e32 v87, 0x3e0293ee, v72
	v_cndmask_b32_e64 v189, v206, v86, s[68:69]
	v_cndmask_b32_e64 v188, v206, v85, s[64:65]
	v_max3_f32 v66, v66, v186, v187
	v_fmac_f32_e32 v90, 0x3e0293ee, v75
	v_fmac_f32_e32 v89, 0x3e0293ee, v74
	v_cndmask_b32_e64 v191, v206, v88, s[76:77]
	v_cndmask_b32_e64 v190, v206, v87, s[72:73]
	v_max3_f32 v66, v66, v188, v189
	v_fmac_f32_e32 v92, 0x3e0293ee, v77
	v_fmac_f32_e32 v91, 0x3e0293ee, v76
	v_cndmask_b32_e64 v193, v206, v90, s[84:85]
	v_cndmask_b32_e64 v192, v206, v89, s[80:81]
	v_max3_f32 v66, v66, v190, v191
	v_fmac_f32_e32 v93, 0x3e0293ee, v78
	v_cndmask_b32_e64 v195, v206, v92, s[92:93]
	v_cndmask_b32_e64 v194, v206, v91, s[88:89]
	v_max3_f32 v66, v66, v192, v193
	s_waitcnt lgkmcnt(1)
	v_fmac_f32_e32 v95, 0x3e0293ee, v80
	v_cndmask_b32_e64 v196, v206, v93, s[96:97]
	s_waitcnt lgkmcnt(0)
	v_fmac_f32_e32 v94, 0x3e0293ee, v81
	v_max3_f32 v66, v66, v194, v195
	v_cndmask_b32_e64 v234, v206, v95, s[8:9]
	v_cndmask_b32_e64 v154, v206, v94, s[12:13]
	v_max3_f32 v66, v66, v196, v197
	v_max3_f32 v66, v66, v234, v154
	v_mov_b32_e32 v67, v66
	s_nop 1
	v_permlane32_swap_b32_e32 v66, v67
	v_max_f32_e32 v67, v67, v67
	v_max_f32_e32 v66, v66, v66
	v_max_f32_e32 v235, v66, v67
	v_sub_f32_e32 v66, v235, v231
	s_mov_b32 s0, 0x4138aa3b
	v_cmp_ge_f32_e32 vcc, s0, v66
	s_cmp_eq_u64 vcc, exec
	s_cselect_b64 s[0:1], -1, 0
